# attention: LDS fragment reads pipelined 3-deep in PV and score MFMA chains; shorter grid-barrier poll sleep; counted vmcnt in cmp/skinny loops
# speedup vs baseline: 1.0161x; 1.0161x over previous
.LBB0_93:
	v_lshl_add_u64 v[44:45], v[16:17], 0, s[14:15]
	s_mov_b32 s5, 0x13c40000
	v_add_co_u32_e64 v24, s[12:13], s5, v44
	v_lshl_add_u64 v[30:31], v[22:23], 0, s[14:15]
	s_nop 0
	v_addc_co_u32_e64 v25, s[12:13], 0, v45, s[12:13]
	s_mov_b32 s5, 0x13c50000
	v_add_co_u32_e64 v26, s[12:13], s5, v44
	s_nop 1
	v_addc_co_u32_e64 v27, s[12:13], 0, v45, s[12:13]
	s_mov_b32 s5, 0x13c60000
	v_add_co_u32_e64 v28, s[12:13], s5, v44
	s_nop 1
	v_addc_co_u32_e64 v29, s[12:13], 0, v45, s[12:13]
	global_load_dwordx4 v[52:55], v[30:31], off offset:-256
	global_load_dwordx4 v[84:87], v[24:25], off
	global_load_dwordx4 v[116:119], v[26:27], off
	global_load_dwordx4 v[164:167], v[28:29], off
	global_load_dwordx4 v[56:59], v[30:31], off offset:-192
	global_load_dwordx4 v[88:91], v[24:25], off offset:64
	global_load_dwordx4 v[120:123], v[26:27], off offset:64
	global_load_dwordx4 v[168:171], v[28:29], off offset:64
	global_load_dwordx4 v[60:63], v[30:31], off offset:-128
	global_load_dwordx4 v[92:95], v[24:25], off offset:128
	global_load_dwordx4 v[124:127], v[26:27], off offset:128
	global_load_dwordx4 v[172:175], v[28:29], off offset:128
	global_load_dwordx4 v[64:67], v[30:31], off offset:-64
	global_load_dwordx4 v[96:99], v[24:25], off offset:192
	global_load_dwordx4 v[128:131], v[26:27], off offset:192
	global_load_dwordx4 v[176:179], v[28:29], off offset:192
	global_load_dwordx4 v[68:71], v[30:31], off
	global_load_dwordx4 v[100:103], v[24:25], off offset:256
	global_load_dwordx4 v[132:135], v[26:27], off offset:256
	global_load_dwordx4 v[180:183], v[28:29], off offset:256
	global_load_dwordx4 v[72:75], v[30:31], off offset:64
	global_load_dwordx4 v[104:107], v[24:25], off offset:320
	global_load_dwordx4 v[136:139], v[26:27], off offset:320
	global_load_dwordx4 v[196:199], v[28:29], off offset:320
	global_load_dwordx4 v[76:79], v[30:31], off offset:128
	global_load_dwordx4 v[108:111], v[24:25], off offset:384
	global_load_dwordx4 v[140:143], v[26:27], off offset:384
	global_load_dwordx4 v[200:203], v[28:29], off offset:384
	global_load_dwordx4 v[80:83], v[30:31], off offset:192
	global_load_dwordx4 v[112:115], v[24:25], off offset:448
	global_load_dwordx4 v[144:147], v[26:27], off offset:448
	global_load_dwordx4 v[204:207], v[28:29], off offset:448
	s_add_u32 s14, s14, 0x200
	s_addc_u32 s15, s15, 0
	s_cmpk_eq_i32 s14, 0x800
	s_waitcnt vmcnt(28)
	v_mfma_f32_16x16x32_bf16 v[10:13], v[84:87], v[52:55], v[10:13]
	v_mfma_f32_16x16x32_bf16 v[6:9], v[116:119], v[52:55], v[6:9]
	v_mfma_f32_16x16x32_bf16 v[2:5], v[164:167], v[52:55], v[2:5]
	s_waitcnt vmcnt(24)
	v_mfma_f32_16x16x32_bf16 v[10:13], v[88:91], v[56:59], v[10:13]
	v_mfma_f32_16x16x32_bf16 v[6:9], v[120:123], v[56:59], v[6:9]
	v_mfma_f32_16x16x32_bf16 v[2:5], v[168:171], v[56:59], v[2:5]
	s_waitcnt vmcnt(20)
	v_mfma_f32_16x16x32_bf16 v[10:13], v[92:95], v[60:63], v[10:13]
	v_mfma_f32_16x16x32_bf16 v[6:9], v[124:127], v[60:63], v[6:9]
	v_mfma_f32_16x16x32_bf16 v[2:5], v[172:175], v[60:63], v[2:5]
	s_waitcnt vmcnt(16)
	v_mfma_f32_16x16x32_bf16 v[10:13], v[96:99], v[64:67], v[10:13]
	v_mfma_f32_16x16x32_bf16 v[6:9], v[128:131], v[64:67], v[6:9]
	v_mfma_f32_16x16x32_bf16 v[2:5], v[176:179], v[64:67], v[2:5]
	s_waitcnt vmcnt(12)
	v_mfma_f32_16x16x32_bf16 v[10:13], v[100:103], v[68:71], v[10:13]
	v_mfma_f32_16x16x32_bf16 v[6:9], v[132:135], v[68:71], v[6:9]
	v_mfma_f32_16x16x32_bf16 v[2:5], v[180:183], v[68:71], v[2:5]
	s_waitcnt vmcnt(8)
	v_mfma_f32_16x16x32_bf16 v[10:13], v[104:107], v[72:75], v[10:13]
	v_mfma_f32_16x16x32_bf16 v[6:9], v[136:139], v[72:75], v[6:9]
	v_mfma_f32_16x16x32_bf16 v[2:5], v[196:199], v[72:75], v[2:5]
	s_waitcnt vmcnt(4)
	v_mfma_f32_16x16x32_bf16 v[10:13], v[108:111], v[76:79], v[10:13]
	v_mfma_f32_16x16x32_bf16 v[6:9], v[140:143], v[76:79], v[6:9]
	v_mfma_f32_16x16x32_bf16 v[2:5], v[200:203], v[76:79], v[2:5]
	s_waitcnt vmcnt(0)
	v_mfma_f32_16x16x32_bf16 v[10:13], v[112:115], v[80:83], v[10:13]
	v_mfma_f32_16x16x32_bf16 v[6:9], v[144:147], v[80:83], v[6:9]
	v_mfma_f32_16x16x32_bf16 v[2:5], v[204:207], v[80:83], v[2:5]
	s_cbranch_scc0 .LBB0_93
	s_nop 1
	s_branch .Lmy_pad_sk3
	s_nop 0
	s_nop 0
	s_nop 0
	s_nop 0
	s_nop 0
	s_nop 0
	s_nop 0
	s_nop 0
	s_nop 0
	s_nop 0
	s_nop 0
.Lmy_pad_sk3:
	s_and_saveexec_b64 s[12:13], s[10:11]
	s_cbranch_execz .LBB0_96
	s_nop 0
	ds_write_b128 v33, v[10:13]
	ds_write_b128 v33, v[6:9] offset:1024
	s_nop 1
	ds_write_b128 v33, v[2:5] offset:2048

.LBB0_110:
	ds_read_b128 v[114:117], v183
	ds_read_b128 v[122:125], v183 offset:64
	v_cmp_lt_i32_e64 s[10:11], 0, v182
	v_add_u32_e32 v197, s12, v196
	v_add_u32_e32 v224, 0x11c00, v197
	s_add_i32 s12, s12, 64
	s_mov_b64 s[2:3], 0x4000
	s_add_i32 s13, s13, 1
	v_lshl_add_u64 v[170:171], v[170:171], 0, s[2:3]
	s_waitcnt lgkmcnt(1)
	v_mfma_f32_16x16x32_bf16 v[118:121], v[114:117], v[2:5], 0
	v_lshl_add_u64 v[172:173], v[172:173], 0, s[2:3]
	v_lshl_add_u64 v[174:175], v[174:175], 0, s[6:7]
	v_lshl_add_u64 v[176:177], v[176:177], 0, s[6:7]
	v_mfma_f32_16x16x32_bf16 v[114:117], v[114:117], v[18:21], 0
	ds_read_b128 v[130:133], v183 offset:8768
	s_cmp_eq_u32 s5, s12
	ds_read_b128 v[236:239], v183 offset:13120
	s_waitcnt lgkmcnt(2)
	v_mfma_f32_16x16x32_bf16 v[118:121], v[122:125], v[6:9], v[118:121]
	v_mfma_f32_16x16x32_bf16 v[114:117], v[122:125], v[22:25], v[114:117]
	ds_read_b128 v[122:125], v183 offset:128
	s_waitcnt lgkmcnt(0)
	v_mfma_f32_16x16x32_bf16 v[118:121], v[122:125], v[10:13], v[118:121]
	v_mfma_f32_16x16x32_bf16 v[114:117], v[122:125], v[26:29], v[114:117]
	ds_read_b128 v[122:125], v183 offset:192
	s_waitcnt lgkmcnt(0)
	v_mfma_f32_16x16x32_bf16 v[126:129], v[122:125], v[30:33], v[114:117]
	s_nop 4
	ds_read_b128 v[114:117], v183 offset:4352
	s_nop 1
	v_sub_f32_e32 v126, v126, v185
	v_mfma_f32_16x16x32_bf16 v[220:223], v[122:125], v[14:17], v[118:121]
	ds_read_b128 v[122:125], v183 offset:4416
	v_sub_f32_e32 v127, v127, v185
	v_exp_f32_e32 v126, v126
	s_waitcnt lgkmcnt(1)
	v_mfma_f32_16x16x32_bf16 v[118:121], v[114:117], v[2:5], 0
	v_exp_f32_e32 v127, v127
	s_nop 1
	v_sub_f32_e32 v211, v220, v184
	v_exp_f32_e32 v212, v211
	v_mfma_f32_16x16x32_bf16 v[114:117], v[114:117], v[18:21], 0
	v_sub_f32_e32 v211, v221, v184
	v_exp_f32_e32 v213, v211
	v_pk_mul_f32 v[126:127], v[168:169], v[126:127]
	s_waitcnt lgkmcnt(0)
	v_mfma_f32_16x16x32_bf16 v[118:121], v[122:125], v[6:9], v[118:121]
	v_mul_f32_e64 v212, v150, v212
	v_mul_f32_e64 v213, v151, v213
	v_cndmask_b32_e64 v211, 0, v213, s[10:11]
	v_mfma_f32_16x16x32_bf16 v[114:117], v[122:125], v[22:25], v[114:117]
	ds_read_b128 v[122:125], v183 offset:4480
	v_sub_f32_e32 v213, v222, v184
	v_exp_f32_e32 v220, v213
	s_waitcnt lgkmcnt(0)
	v_mfma_f32_16x16x32_bf16 v[118:121], v[122:125], v[10:13], v[118:121]
	v_sub_f32_e32 v213, v223, v184
	v_exp_f32_e32 v221, v213
	v_cmp_lt_i32_e64 s[10:11], -1, v182
	v_mfma_f32_16x16x32_bf16 v[114:117], v[122:125], v[26:29], v[114:117]
	ds_read_b128 v[122:125], v183 offset:4544
	v_cndmask_b32_e64 v212, 0, v212, s[10:11]
	v_pk_mul_f32 v[220:221], v[150:151], v[220:221]
	s_waitcnt lgkmcnt(0)
	v_mfma_f32_16x16x32_bf16 v[138:141], v[122:125], v[14:17], v[118:121]
	v_cmp_lt_i32_e64 s[10:11], 2, v182
	s_nop 6
	v_sub_f32_e32 v138, v138, v184
	v_mfma_f32_16x16x32_bf16 v[122:125], v[122:125], v[30:33], v[114:117]
	v_cndmask_b32_e64 v213, 0, v221, s[10:11]
	v_mul_f32_e32 v222, 0.5, v213
	v_cndmask_b32_e32 v179, v222, v179, vcc
	ds_read_b128 v[114:117], v183 offset:8704
	s_waitcnt lgkmcnt(0)
	v_mfma_f32_16x16x32_bf16 v[118:121], v[114:117], v[2:5], 0
	v_cmp_lt_i32_e64 s[10:11], 1, v182
	ds_bpermute_b32 v179, v195, v179
	v_sub_f32_e32 v139, v139, v184
	v_mfma_f32_16x16x32_bf16 v[114:117], v[114:117], v[18:21], 0
	v_exp_f32_e32 v138, v138
	v_exp_f32_e32 v139, v139
	v_sub_f32_e32 v140, v140, v184
	v_mfma_f32_16x16x32_bf16 v[118:121], v[130:133], v[6:9], v[118:121]
	v_sub_f32_e32 v141, v141, v184
	v_exp_f32_e32 v140, v140
	v_exp_f32_e32 v141, v141
	v_mfma_f32_16x16x32_bf16 v[114:117], v[130:133], v[22:25], v[114:117]
	ds_read_b128 v[130:133], v183 offset:8832
	v_sub_f32_e32 v122, v122, v185
	v_sub_f32_e32 v123, v123, v185
	s_waitcnt lgkmcnt(0)
	v_mfma_f32_16x16x32_bf16 v[118:121], v[130:133], v[10:13], v[118:121]
	v_exp_f32_e32 v122, v122
	v_exp_f32_e32 v123, v123
	v_mfma_f32_16x16x32_bf16 v[114:117], v[130:133], v[26:29], v[114:117]
	ds_read_b128 v[130:133], v183 offset:8896
	v_pk_mul_f32 v[122:123], v[168:169], v[122:123]
	s_waitcnt lgkmcnt(0)
	v_mfma_f32_16x16x32_bf16 v[134:137], v[130:133], v[14:17], v[118:121]
	s_nop 7
	v_sub_f32_e32 v134, v134, v184
	v_mfma_f32_16x16x32_bf16 v[118:121], v[130:133], v[30:33], v[114:117]
	v_sub_f32_e32 v135, v135, v184
	v_exp_f32_e32 v134, v134
	v_exp_f32_e32 v135, v135
	ds_read_b128 v[114:117], v183 offset:13056
	s_waitcnt lgkmcnt(0)
	v_mfma_f32_16x16x32_bf16 v[130:133], v[114:117], v[2:5], 0
	v_sub_f32_e32 v136, v136, v184
	v_sub_f32_e32 v137, v137, v184
	v_exp_f32_e32 v136, v136
	v_mfma_f32_16x16x32_bf16 v[114:117], v[114:117], v[18:21], 0
	v_exp_f32_e32 v137, v137
	v_sub_f32_e32 v118, v118, v185
	v_sub_f32_e32 v119, v119, v185
	v_mfma_f32_16x16x32_bf16 v[130:133], v[236:239], v[6:9], v[130:133]
	v_exp_f32_e32 v118, v118
	v_exp_f32_e32 v119, v119
	v_mfma_f32_16x16x32_bf16 v[114:117], v[236:239], v[22:25], v[114:117]
	ds_read_b128 v[236:239], v183 offset:13184
	v_pk_mul_f32 v[118:119], v[168:169], v[118:119]
	s_waitcnt lgkmcnt(0)
	v_mfma_f32_16x16x32_bf16 v[130:133], v[236:239], v[10:13], v[130:133]
	v_mfma_f32_16x16x32_bf16 v[114:117], v[236:239], v[26:29], v[114:117]
	ds_read_b128 v[236:239], v183 offset:13248
	s_waitcnt lgkmcnt(0)
	v_mfma_f32_16x16x32_bf16 v[130:133], v[236:239], v[14:17], v[130:133]
	s_nop 7
	v_sub_f32_e32 v130, v130, v184
	v_mfma_f32_16x16x32_bf16 v[114:117], v[236:239], v[30:33], v[114:117]
	v_cndmask_b32_e64 v236, 0, v220, s[10:11]
	v_add_f32_e32 v220, v212, v211
	v_add_f32_e32 v220, v236, v220
	v_add_f32_e32 v220, v213, v220
	v_fmac_f32_e32 v220, -0.5, v213
	v_add_f32_e32 v179, v220, v179
	v_pk_mul_f32 v[220:221], v[150:151], v[138:139]
	v_cmp_lt_i32_e64 s[10:11], 16, v182
	ds_write_b32 v224, v179
	v_sub_f32_e32 v131, v131, v184
	v_cndmask_b32_e64 v138, 0, v221, s[10:11]
	v_cmp_lt_i32_e64 s[10:11], 15, v182
	v_exp_f32_e32 v130, v130
	v_exp_f32_e32 v131, v131
	v_cndmask_b32_e64 v139, 0, v220, s[10:11]
	v_pk_mul_f32 v[220:221], v[150:151], v[140:141]
	v_cmp_lt_i32_e64 s[10:11], 18, v182
	v_add_f32_e32 v179, v139, v138
	v_pk_mul_f32 v[130:131], v[150:151], v[130:131]
	v_cndmask_b32_e64 v140, 0, v221, s[10:11]
	v_cmp_lt_i32_e64 s[10:11], 17, v182
	v_mul_f32_e32 v223, 0.5, v140
	v_sub_f32_e32 v114, v114, v185
	v_cndmask_b32_e64 v141, 0, v220, s[10:11]
	v_cndmask_b32_e32 v220, v223, v222, vcc
	ds_bpermute_b32 v220, v195, v220
	v_add_f32_e32 v179, v141, v179
	v_add_f32_e32 v179, v140, v179
	v_fmac_f32_e32 v179, -0.5, v140
	v_cmp_lt_i32_e64 s[10:11], 32, v182
	s_waitcnt lgkmcnt(0)
	v_add_f32_e32 v179, v179, v220
	v_add_u32_e32 v220, 0x11c10, v197
	ds_write_b32 v220, v179
	v_pk_mul_f32 v[220:221], v[150:151], v[134:135]
	v_sub_f32_e32 v115, v115, v185
	v_cndmask_b32_e64 v134, 0, v221, s[10:11]
	v_cmp_lt_i32_e64 s[10:11], 31, v182
	v_exp_f32_e32 v114, v114
	v_exp_f32_e32 v115, v115
	v_cndmask_b32_e64 v135, 0, v220, s[10:11]
	v_pk_mul_f32 v[220:221], v[150:151], v[136:137]
	v_cmp_lt_i32_e64 s[10:11], 34, v182
	v_add_f32_e32 v179, v135, v134
	v_pk_mul_f32 v[114:115], v[168:169], v[114:115]
	v_cndmask_b32_e64 v136, 0, v221, s[10:11]
	v_cmp_lt_i32_e64 s[10:11], 33, v182
	s_nop 1
	v_cndmask_b32_e64 v137, 0, v220, s[10:11]
	v_mul_f32_e32 v220, 0.5, v136
	v_cndmask_b32_e32 v221, v220, v223, vcc
	ds_bpermute_b32 v221, v195, v221
	v_add_f32_e32 v179, v137, v179
	v_add_f32_e32 v179, v136, v179
	v_fmac_f32_e32 v179, -0.5, v136
	v_cmp_lt_i32_e64 s[10:11], 48, v182
	s_waitcnt lgkmcnt(0)
	v_add_f32_e32 v179, v179, v221
	v_add_u32_e32 v221, 0x11c20, v197
	ds_write_b32 v221, v179
	v_cndmask_b32_e64 v221, 0, v131, s[10:11]
	v_cmp_lt_i32_e64 s[10:11], 47, v182
	v_sub_f32_e32 v131, v133, v184
	v_exp_f32_e32 v131, v131
	v_cndmask_b32_e64 v222, 0, v130, s[10:11]
	v_sub_f32_e32 v130, v132, v184
	v_exp_f32_e32 v130, v130
	v_cmp_lt_i32_e64 s[10:11], 50, v182
	v_add_u32_e32 v133, 0x11c30, v197
	v_pk_mul_f32 v[130:131], v[150:151], v[130:131]
	s_nop 0
	v_cndmask_b32_e64 v131, 0, v131, s[10:11]
	v_cmp_lt_i32_e64 s[10:11], 49, v182
	v_subrev_u32_e32 v182, 64, v182
	s_nop 0
	v_cndmask_b32_e64 v132, 0, v130, s[10:11]
	v_cmp_lt_i32_e64 s[10:11], 0, v159
	v_add_u32_e32 v130, 0x12c00, v197
	s_nop 0
	v_cndmask_b32_e64 v223, 0, v127, s[10:11]
	v_cmp_lt_i32_e64 s[10:11], -1, v159
	v_sub_f32_e32 v127, v129, v185
	v_exp_f32_e32 v127, v127
	v_cndmask_b32_e64 v224, 0, v126, s[10:11]
	v_sub_f32_e32 v126, v128, v185
	v_exp_f32_e32 v126, v126
	v_cmp_lt_i32_e64 s[10:11], 2, v159
	v_add_f32_e32 v128, v224, v223
	v_pk_mul_f32 v[126:127], v[168:169], v[126:127]
	s_nop 0
	v_cndmask_b32_e64 v127, 0, v127, s[10:11]
	v_mul_f32_e32 v129, 0.5, v127
	v_cndmask_b32_e32 v178, v129, v178, vcc
	v_cmp_lt_i32_e64 s[10:11], 1, v159
	ds_bpermute_b32 v178, v195, v178
	s_nop 0
	v_cndmask_b32_e64 v126, 0, v126, s[10:11]
	v_add_f32_e32 v128, v126, v128
	v_add_f32_e32 v128, v127, v128
	v_fmac_f32_e32 v128, -0.5, v127
	s_waitcnt lgkmcnt(0)
	v_add_f32_e32 v128, v128, v178
	v_cmp_lt_i32_e64 s[10:11], 16, v159
	ds_write_b32 v130, v128
	s_nop 0
	v_cndmask_b32_e64 v128, 0, v123, s[10:11]
	v_cmp_lt_i32_e64 s[10:11], 15, v159
	v_sub_f32_e32 v123, v125, v185
	v_exp_f32_e32 v123, v123
	v_cndmask_b32_e64 v225, 0, v122, s[10:11]
	v_sub_f32_e32 v122, v124, v185
	v_exp_f32_e32 v122, v122
	v_cmp_lt_i32_e64 s[10:11], 18, v159
	v_add_f32_e32 v124, v225, v128
	v_pk_mul_f32 v[122:123], v[168:169], v[122:123]
	s_nop 0
	v_cndmask_b32_e64 v123, 0, v123, s[10:11]
	v_mul_f32_e32 v125, 0.5, v123
	v_cndmask_b32_e32 v129, v125, v129, vcc
	v_cmp_lt_i32_e64 s[10:11], 17, v159
	ds_bpermute_b32 v129, v195, v129
	s_nop 0
	v_cndmask_b32_e64 v122, 0, v122, s[10:11]
	v_add_f32_e32 v124, v122, v124
	v_add_f32_e32 v124, v123, v124
	v_fmac_f32_e32 v124, -0.5, v123
	s_waitcnt lgkmcnt(0)
	v_add_f32_e32 v124, v124, v129
	v_add_u32_e32 v129, 0x12c10, v197
	v_cmp_lt_i32_e64 s[10:11], 32, v159
	ds_write_b32 v129, v124
	s_nop 0
	v_cndmask_b32_e64 v129, 0, v119, s[10:11]
	v_cmp_lt_i32_e64 s[10:11], 31, v159
	v_sub_f32_e32 v119, v121, v185
	v_exp_f32_e32 v119, v119
	v_cndmask_b32_e64 v226, 0, v118, s[10:11]
	v_sub_f32_e32 v118, v120, v185
	v_exp_f32_e32 v118, v118
	v_cmp_lt_i32_e64 s[10:11], 34, v159
	v_cvt_pk_bf16_f32 v121, v122, v123
	v_pk_mul_f32 v[118:119], v[168:169], v[118:119]
	s_nop 0
	v_cndmask_b32_e64 v235, 0, v119, s[10:11]
	v_cmp_lt_i32_e64 s[10:11], 33, v159
	v_mul_f32_e32 v119, 0.5, v235
	v_cndmask_b32_e32 v120, v119, v125, vcc
	v_cndmask_b32_e64 v237, 0, v118, s[10:11]
	v_cmp_lt_i32_e64 s[10:11], 48, v159
	ds_bpermute_b32 v120, v195, v120
	v_add_f32_e32 v118, v226, v129
	v_cndmask_b32_e64 v238, 0, v115, s[10:11]
	v_cmp_lt_i32_e64 s[10:11], 47, v159
	v_sub_f32_e32 v115, v117, v185
	v_exp_f32_e32 v115, v115
	v_cndmask_b32_e64 v239, 0, v114, s[10:11]
	v_sub_f32_e32 v114, v116, v185
	v_exp_f32_e32 v114, v114
	v_cmp_lt_i32_e64 s[10:11], 50, v159
	v_add_f32_e32 v118, v237, v118
	v_add_f32_e32 v118, v235, v118
	v_pk_mul_f32 v[114:115], v[168:169], v[114:115]
	v_fmac_f32_e32 v118, -0.5, v235
	v_cndmask_b32_e64 v130, 0, v115, s[10:11]
	v_cmp_lt_i32_e64 s[10:11], 49, v159
	v_pk_mul_f32 v[178:179], v[130:131], 0.5 op_sel_hi:[1,0]
	v_add_f32_e32 v115, v222, v221
	v_cndmask_b32_e64 v240, 0, v114, s[10:11]
	v_cndmask_b32_e32 v114, v179, v220, vcc
	ds_bpermute_b32 v114, v195, v114
	v_add_f32_e32 v115, v132, v115
	v_add_f32_e32 v115, v131, v115
	v_sub_f32_e32 v115, v115, v179
	s_waitcnt lgkmcnt(1)
	v_add_f32_e32 v118, v118, v120
	s_waitcnt lgkmcnt(0)
	v_add_f32_e32 v114, v115, v114
	ds_write_b32 v133, v114
	v_cndmask_b32_e32 v114, v178, v119, vcc
	ds_bpermute_b32 v114, v195, v114
	v_add_f32_e32 v115, v239, v238
	v_add_f32_e32 v115, v240, v115
	v_add_f32_e32 v115, v130, v115
	v_sub_f32_e32 v115, v115, v178
	v_add_u32_e32 v120, 0x12c20, v197
	s_waitcnt lgkmcnt(0)
	v_add_f32_e32 v114, v115, v114
	v_add_u32_e32 v115, 0x12c30, v197
	ds_write_b32 v120, v118
	ds_write_b32 v115, v114
	v_cvt_pk_bf16_f32 v119, v126, v127
	v_add_u32_e32 v126, v192, v204
	ds_read_b128 v[122:125], v126 offset:17408
	ds_read_b128 v[244:247], v126 offset:19712
	ds_read_b128 v[248:251], v126 offset:22016
	v_cvt_pk_bf16_f32 v114, v212, v211
	v_cvt_pk_bf16_f32 v115, v236, v213
	v_cvt_pk_bf16_f32 v116, v139, v138
	v_cvt_pk_bf16_f32 v117, v141, v140
	v_cvt_pk_bf16_f32 v118, v224, v223
	v_cvt_pk_bf16_f32 v120, v225, v128
	s_waitcnt lgkmcnt(2)
	v_mfma_f32_16x16x32_bf16 v[102:105], v[122:125], v[114:117], v[102:105]
	v_subrev_u32_e32 v159, 64, v159
	v_mfma_f32_16x16x32_bf16 v[74:77], v[122:125], v[118:121], v[74:77]
	ds_read_b128 v[122:125], v126 offset:24320
	s_waitcnt lgkmcnt(2)
	v_mfma_f32_16x16x32_bf16 v[106:109], v[244:247], v[114:117], v[106:109]
	v_mfma_f32_16x16x32_bf16 v[78:81], v[244:247], v[118:121], v[78:81]
	ds_read_b128 v[244:247], v126 offset:26624
	s_waitcnt lgkmcnt(2)
	v_mfma_f32_16x16x32_bf16 v[98:101], v[248:251], v[114:117], v[98:101]
	v_mfma_f32_16x16x32_bf16 v[70:73], v[248:251], v[118:121], v[70:73]
	ds_read_b128 v[248:251], v126 offset:28928
	s_waitcnt lgkmcnt(2)
	v_mfma_f32_16x16x32_bf16 v[94:97], v[122:125], v[114:117], v[94:97]
	v_mfma_f32_16x16x32_bf16 v[66:69], v[122:125], v[118:121], v[66:69]
	ds_read_b128 v[122:125], v126 offset:31232
	s_waitcnt lgkmcnt(2)
	v_mfma_f32_16x16x32_bf16 v[90:93], v[244:247], v[114:117], v[90:93]
	v_mfma_f32_16x16x32_bf16 v[62:65], v[244:247], v[118:121], v[62:65]
	ds_read_b128 v[244:247], v126 offset:33536
	s_waitcnt lgkmcnt(2)
	v_mfma_f32_16x16x32_bf16 v[86:89], v[248:251], v[114:117], v[86:89]
	v_mfma_f32_16x16x32_bf16 v[54:57], v[248:251], v[118:121], v[54:57]
	ds_read_b128 v[248:251], v126 offset:17472
	s_waitcnt lgkmcnt(2)
	v_mfma_f32_16x16x32_bf16 v[82:85], v[122:125], v[114:117], v[82:85]
	v_mfma_f32_16x16x32_bf16 v[58:61], v[122:125], v[118:121], v[58:61]
	ds_read_b128 v[122:125], v126 offset:19776
	s_waitcnt lgkmcnt(2)
	v_mfma_f32_16x16x32_bf16 v[110:113], v[244:247], v[114:117], v[110:113]
	v_cvt_pk_bf16_f32 v114, v135, v134
	v_cvt_pk_bf16_f32 v115, v137, v136
	v_cvt_pk_bf16_f32 v116, v222, v221
	v_mfma_f32_16x16x32_bf16 v[50:53], v[244:247], v[118:121], v[50:53]
	ds_read_b128 v[244:247], v126 offset:22080
	v_cvt_pk_bf16_f32 v117, v132, v131
	v_cvt_pk_bf16_f32 v118, v226, v129
	v_cvt_pk_bf16_f32 v119, v237, v235
	v_cvt_pk_bf16_f32 v120, v239, v238
	v_cvt_pk_bf16_f32 v121, v240, v130
	s_waitcnt lgkmcnt(2)
	v_mfma_f32_16x16x32_bf16 v[102:105], v[248:251], v[114:117], v[102:105]
	v_mfma_f32_16x16x32_bf16 v[74:77], v[248:251], v[118:121], v[74:77]
	ds_read_b128 v[248:251], v126 offset:24384
	s_waitcnt lgkmcnt(2)
	v_mfma_f32_16x16x32_bf16 v[106:109], v[122:125], v[114:117], v[106:109]
	v_mfma_f32_16x16x32_bf16 v[78:81], v[122:125], v[118:121], v[78:81]
	ds_read_b128 v[122:125], v126 offset:26688
	s_waitcnt lgkmcnt(2)
	v_mfma_f32_16x16x32_bf16 v[98:101], v[244:247], v[114:117], v[98:101]
	v_mfma_f32_16x16x32_bf16 v[70:73], v[244:247], v[118:121], v[70:73]
	ds_read_b128 v[244:247], v126 offset:28992
	s_waitcnt lgkmcnt(2)
	v_mfma_f32_16x16x32_bf16 v[94:97], v[248:251], v[114:117], v[94:97]
	v_mfma_f32_16x16x32_bf16 v[66:69], v[248:251], v[118:121], v[66:69]
	ds_read_b128 v[248:251], v126 offset:31296
	s_waitcnt lgkmcnt(2)
	v_mfma_f32_16x16x32_bf16 v[90:93], v[122:125], v[114:117], v[90:93]
	v_mfma_f32_16x16x32_bf16 v[62:65], v[122:125], v[118:121], v[62:65]
	ds_read_b128 v[122:125], v126 offset:33600
	s_waitcnt lgkmcnt(2)
	v_mfma_f32_16x16x32_bf16 v[86:89], v[244:247], v[114:117], v[86:89]
	v_mfma_f32_16x16x32_bf16 v[54:57], v[244:247], v[118:121], v[54:57]
	s_waitcnt lgkmcnt(1)
	v_mfma_f32_16x16x32_bf16 v[82:85], v[248:251], v[114:117], v[82:85]
	v_mfma_f32_16x16x32_bf16 v[58:61], v[248:251], v[118:121], v[58:61]
	s_waitcnt lgkmcnt(0)
	v_mfma_f32_16x16x32_bf16 v[110:113], v[122:125], v[114:117], v[110:113]
	v_mfma_f32_16x16x32_bf16 v[50:53], v[122:125], v[118:121], v[50:53]
	s_cbranch_scc1 .LBB0_113

.LBB0_127:
	s_lshl_b64 s[12:13], 1, s24
	s_cmp_ge_i32 s24, s40
	v_lshl_or_b32 v1, s24, 6, v207
	s_cselect_b64 s[24:25], -1, 0
	s_cmp_eq_u32 s31, 0
	s_cselect_b32 s14, 0, 0x11c00
	v_sub_u32_e32 v211, 0, v1
	v_add_u32_e32 v1, s14, v192
	v_and_b32_e32 v115, s13, v181
	v_and_b32_e32 v114, s12, v180
	v_add_u32_e32 v212, v1, v198
	v_cmp_ne_u64_e64 s[10:11], 0, v[114:115]
	ds_read_b128 v[220:223], v212
	ds_read_b128 v[244:247], v212 offset:64
	ds_read_b128 v[248:251], v212 offset:128
	s_and_b64 vcc, exec, s[24:25]
	s_waitcnt lgkmcnt(2)
	v_mfma_f32_16x16x32_bf16 v[130:133], v[220:223], v[2:5], 0
	v_mfma_f32_16x16x32_bf16 v[114:117], v[220:223], v[18:21], 0
	ds_read_b128 v[220:223], v212 offset:192
	s_waitcnt lgkmcnt(2)
	v_mfma_f32_16x16x32_bf16 v[130:133], v[244:247], v[6:9], v[130:133]
	v_mfma_f32_16x16x32_bf16 v[114:117], v[244:247], v[22:25], v[114:117]
	ds_read_b128 v[244:247], v212 offset:4352
	s_waitcnt lgkmcnt(2)
	v_mfma_f32_16x16x32_bf16 v[130:133], v[248:251], v[10:13], v[130:133]
	v_mfma_f32_16x16x32_bf16 v[114:117], v[248:251], v[26:29], v[114:117]
	ds_read_b128 v[248:251], v212 offset:4416
	s_waitcnt lgkmcnt(2)
	v_mfma_f32_16x16x32_bf16 v[130:133], v[220:223], v[14:17], v[130:133]
	v_mfma_f32_16x16x32_bf16 v[114:117], v[220:223], v[30:33], v[114:117]
	ds_read_b128 v[220:223], v212 offset:4480
	s_waitcnt lgkmcnt(2)
	v_mfma_f32_16x16x32_bf16 v[134:137], v[244:247], v[2:5], 0
	v_mfma_f32_16x16x32_bf16 v[118:121], v[244:247], v[18:21], 0
	ds_read_b128 v[244:247], v212 offset:4544
	s_waitcnt lgkmcnt(2)
	v_mfma_f32_16x16x32_bf16 v[134:137], v[248:251], v[6:9], v[134:137]
	v_mfma_f32_16x16x32_bf16 v[118:121], v[248:251], v[22:25], v[118:121]
	ds_read_b128 v[248:251], v212 offset:8704
	s_waitcnt lgkmcnt(2)
	v_mfma_f32_16x16x32_bf16 v[134:137], v[220:223], v[10:13], v[134:137]
	v_mfma_f32_16x16x32_bf16 v[118:121], v[220:223], v[26:29], v[118:121]
	ds_read_b128 v[220:223], v212 offset:8768
	s_waitcnt lgkmcnt(2)
	v_mfma_f32_16x16x32_bf16 v[134:137], v[244:247], v[14:17], v[134:137]
	v_mfma_f32_16x16x32_bf16 v[118:121], v[244:247], v[30:33], v[118:121]
	ds_read_b128 v[244:247], v212 offset:8832
	s_waitcnt lgkmcnt(2)
	v_mfma_f32_16x16x32_bf16 v[138:141], v[248:251], v[2:5], 0
	v_mfma_f32_16x16x32_bf16 v[122:125], v[248:251], v[18:21], 0
	ds_read_b128 v[248:251], v212 offset:8896
	s_waitcnt lgkmcnt(2)
	v_mfma_f32_16x16x32_bf16 v[138:141], v[220:223], v[6:9], v[138:141]
	v_mfma_f32_16x16x32_bf16 v[122:125], v[220:223], v[22:25], v[122:125]
	ds_read_b128 v[220:223], v212 offset:13056
	s_waitcnt lgkmcnt(2)
	v_mfma_f32_16x16x32_bf16 v[138:141], v[244:247], v[10:13], v[138:141]
	v_mfma_f32_16x16x32_bf16 v[122:125], v[244:247], v[26:29], v[122:125]
	ds_read_b128 v[244:247], v212 offset:13120
	s_waitcnt lgkmcnt(2)
	v_mfma_f32_16x16x32_bf16 v[138:141], v[248:251], v[14:17], v[138:141]
	v_mfma_f32_16x16x32_bf16 v[122:125], v[248:251], v[30:33], v[122:125]
	ds_read_b128 v[248:251], v212 offset:13184
	s_waitcnt lgkmcnt(2)
	v_mfma_f32_16x16x32_bf16 v[142:145], v[220:223], v[2:5], 0
	v_mfma_f32_16x16x32_bf16 v[126:129], v[220:223], v[18:21], 0
	ds_read_b128 v[220:223], v212 offset:13248
	s_waitcnt lgkmcnt(2)
	v_mfma_f32_16x16x32_bf16 v[142:145], v[244:247], v[6:9], v[142:145]
	v_mfma_f32_16x16x32_bf16 v[126:129], v[244:247], v[22:25], v[126:129]
	s_waitcnt lgkmcnt(1)
	v_mfma_f32_16x16x32_bf16 v[142:145], v[248:251], v[10:13], v[142:145]
	v_mfma_f32_16x16x32_bf16 v[126:129], v[248:251], v[26:29], v[126:129]
	s_waitcnt lgkmcnt(0)
	v_mfma_f32_16x16x32_bf16 v[142:145], v[220:223], v[14:17], v[142:145]
	v_mfma_f32_16x16x32_bf16 v[126:129], v[220:223], v[30:33], v[126:129]
	s_cbranch_vccz .LBB0_129
	v_add_u32_e32 v212, v211, v208
	v_cndmask_b32_e64 v220, v229, 0, s[10:11]
	v_cndmask_b32_e64 v213, v228, 0, s[10:11]
	v_cmp_lt_i32_e32 vcc, v212, v220
	v_sub_u32_e32 v212, v212, v220
	s_nop 0
	v_cndmask_b32_e32 v213, v213, v230, vcc
	v_cndmask_b32_e64 v212, v212, 0, vcc
	v_cmp_le_u32_e32 vcc, v213, v212
	v_or_b32_e32 v220, 2, v213
	s_nop 0
	v_cndmask_b32_e32 v130, v227, v130, vcc
	v_cmp_lt_u32_e32 vcc, v213, v212
	s_nop 1
	v_cndmask_b32_e32 v131, v227, v131, vcc
	v_cmp_le_u32_e32 vcc, v220, v212
	v_or_b32_e32 v220, 3, v213
	s_nop 0
	v_cndmask_b32_e32 v132, v227, v132, vcc
	v_cmp_le_u32_e32 vcc, v220, v212
	v_add_u32_e32 v220, 16, v213
	s_nop 0
	v_cndmask_b32_e32 v133, v227, v133, vcc
	v_cmp_le_u32_e32 vcc, v220, v212
	v_add_u32_e32 v220, 17, v213
	s_nop 0
	v_cndmask_b32_e32 v134, v227, v134, vcc
	v_cmp_le_u32_e32 vcc, v220, v212
	v_add_u32_e32 v220, 18, v213
	s_nop 0
	v_cndmask_b32_e32 v135, v227, v135, vcc
	v_cmp_le_u32_e32 vcc, v220, v212
	v_add_u32_e32 v220, 19, v213
	s_nop 0
	v_cndmask_b32_e32 v136, v227, v136, vcc
	v_cmp_le_u32_e32 vcc, v220, v212
	v_add_u32_e32 v220, 32, v213
	s_nop 0
	v_cndmask_b32_e32 v137, v227, v137, vcc
	v_cmp_le_u32_e32 vcc, v220, v212
	v_add_u32_e32 v220, 33, v213
	s_nop 0
	v_cndmask_b32_e32 v138, v227, v138, vcc
	v_cmp_le_u32_e32 vcc, v220, v212
	v_add_u32_e32 v220, 34, v213
	s_nop 0
	v_cndmask_b32_e32 v139, v227, v139, vcc
	v_cmp_le_u32_e32 vcc, v220, v212
	v_add_u32_e32 v220, 35, v213
	s_nop 0
	v_cndmask_b32_e32 v140, v227, v140, vcc
	v_cmp_le_u32_e32 vcc, v220, v212
	v_add_u32_e32 v220, 48, v213
	s_nop 0
	v_cndmask_b32_e32 v141, v227, v141, vcc
	v_cmp_le_u32_e32 vcc, v220, v212
	v_add_u32_e32 v220, 49, v213
	s_nop 0
	v_cndmask_b32_e32 v142, v227, v142, vcc
	v_cmp_le_u32_e32 vcc, v220, v212
	v_add_u32_e32 v220, 50, v213
	v_add_u32_e32 v213, 51, v213
	v_cndmask_b32_e32 v143, v227, v143, vcc
	v_cmp_le_u32_e32 vcc, v220, v212
	s_nop 1
	v_cndmask_b32_e32 v144, v227, v144, vcc
	v_cmp_le_u32_e32 vcc, v213, v212
	s_nop 1
	v_cndmask_b32_e32 v145, v227, v145, vcc

.LBB0_134:
	v_cmp_ngt_f32_e32 vcc, s2, v173
	v_add_u32_e32 v1, v1, v204
	s_nop 0
	v_cndmask_b32_e32 v211, 0, v173, vcc
	s_or_b64 vcc, s[24:25], s[10:11]
	v_cndmask_b32_e32 v211, v231, v211, vcc
	v_sub_f32_e32 v130, v130, v211
	v_exp_f32_e32 v213, v130
	v_sub_f32_e32 v130, v131, v211
	v_exp_f32_e32 v221, v130
	v_sub_f32_e32 v130, v132, v211
	v_exp_f32_e32 v223, v130
	v_sub_f32_e32 v130, v133, v211
	v_exp_f32_e32 v225, v130
	v_sub_f32_e32 v130, v134, v211
	v_exp_f32_e32 v237, v130
	v_sub_f32_e32 v130, v135, v211
	v_exp_f32_e32 v239, v130
	v_sub_f32_e32 v130, v136, v211
	v_exp_f32_e32 v241, v130
	v_sub_f32_e32 v130, v137, v211
	v_exp_f32_e32 v243, v130
	v_sub_f32_e32 v130, v138, v211
	v_exp_f32_e32 v131, v130
	v_sub_f32_e32 v130, v139, v211
	v_exp_f32_e32 v133, v130
	v_sub_f32_e32 v130, v140, v211
	v_exp_f32_e32 v135, v130
	v_sub_f32_e32 v130, v141, v211
	v_exp_f32_e32 v137, v130
	v_sub_f32_e32 v130, v142, v211
	v_exp_f32_e32 v139, v130
	v_sub_f32_e32 v130, v143, v211
	v_exp_f32_e32 v141, v130
	v_sub_f32_e32 v130, v144, v211
	v_exp_f32_e32 v143, v130
	v_sub_f32_e32 v130, v145, v211
	v_cmp_ngt_f32_e32 vcc, s2, v169
	v_exp_f32_e32 v145, v130
	s_nop 0
	v_cndmask_b32_e32 v130, 0, v169, vcc
	s_or_b64 vcc, s[24:25], s[12:13]
	v_cndmask_b32_e32 v144, v231, v130, vcc
	v_sub_f32_e32 v114, v114, v144
	v_exp_f32_e32 v212, v114
	v_sub_f32_e32 v114, v115, v144
	v_exp_f32_e32 v220, v114
	v_sub_f32_e32 v114, v116, v144
	v_exp_f32_e32 v222, v114
	v_sub_f32_e32 v114, v117, v144
	v_exp_f32_e32 v224, v114
	v_sub_f32_e32 v114, v118, v144
	v_exp_f32_e32 v236, v114
	v_sub_f32_e32 v114, v119, v144
	v_exp_f32_e32 v238, v114
	v_sub_f32_e32 v114, v120, v144
	v_exp_f32_e32 v240, v114
	v_sub_f32_e32 v114, v121, v144
	v_exp_f32_e32 v242, v114
	v_pk_add_f32 v[114:115], v[212:213], 0 op_sel_hi:[1,0]
	v_sub_f32_e32 v116, v122, v144
	v_pk_add_f32 v[114:115], v[220:221], v[114:115]
	v_exp_f32_e32 v130, v116
	v_pk_add_f32 v[114:115], v[222:223], v[114:115]
	v_sub_f32_e32 v116, v123, v144
	v_pk_add_f32 v[114:115], v[224:225], v[114:115]
	v_exp_f32_e32 v132, v116
	v_pk_add_f32 v[114:115], v[236:237], v[114:115]
	v_sub_f32_e32 v116, v124, v144
	v_pk_add_f32 v[114:115], v[238:239], v[114:115]
	v_exp_f32_e32 v134, v116
	v_pk_add_f32 v[114:115], v[240:241], v[114:115]
	v_sub_f32_e32 v116, v125, v144
	v_pk_add_f32 v[114:115], v[242:243], v[114:115]
	v_exp_f32_e32 v136, v116
	v_sub_f32_e32 v116, v126, v144
	v_exp_f32_e32 v138, v116
	v_sub_f32_e32 v116, v127, v144
	v_pk_add_f32 v[114:115], v[130:131], v[114:115]
	ds_read_b128 v[122:125], v1 offset:17408
	ds_read_b128 v[244:247], v1 offset:19712
	ds_read_b128 v[248:251], v1 offset:22016
	v_exp_f32_e32 v140, v116
	v_sub_f32_e32 v116, v128, v144
	v_pk_add_f32 v[114:115], v[132:133], v[114:115]
	v_exp_f32_e32 v142, v116
	v_sub_f32_e32 v116, v129, v144
	v_pk_add_f32 v[114:115], v[134:135], v[114:115]
	v_exp_f32_e32 v144, v116
	v_pk_add_f32 v[114:115], v[136:137], v[114:115]
	v_cvt_pk_bf16_f32 v116, v237, v239
	v_pk_add_f32 v[114:115], v[138:139], v[114:115]
	v_cvt_pk_bf16_f32 v117, v241, v243
	v_pk_add_f32 v[114:115], v[140:141], v[114:115]
	v_cvt_pk_bf16_f32 v118, v212, v220
	v_pk_add_f32 v[114:115], v[142:143], v[114:115]
	v_cvt_pk_bf16_f32 v119, v222, v224
	v_pk_add_f32 v[114:115], v[144:145], v[114:115]
	v_cvt_pk_bf16_f32 v120, v236, v238
	v_pk_add_f32 v[196:197], v[196:197], v[114:115]
	v_cvt_pk_bf16_f32 v114, v213, v221
	v_cvt_pk_bf16_f32 v115, v223, v225
	v_cvt_pk_bf16_f32 v121, v240, v242
	s_andn2_b64 vcc, exec, s[20:21]
	s_waitcnt lgkmcnt(2)
	v_mfma_f32_16x16x32_bf16 v[94:97], v[122:125], v[114:117], v[94:97]
	v_mfma_f32_16x16x32_bf16 v[42:45], v[122:125], v[118:121], v[42:45]
	ds_read_b128 v[122:125], v1 offset:24320
	s_waitcnt lgkmcnt(2)
	v_mfma_f32_16x16x32_bf16 v[86:89], v[244:247], v[114:117], v[86:89]
	v_mfma_f32_16x16x32_bf16 v[34:37], v[244:247], v[118:121], v[34:37]
	ds_read_b128 v[244:247], v1 offset:26624
	s_waitcnt lgkmcnt(2)
	v_mfma_f32_16x16x32_bf16 v[82:85], v[248:251], v[114:117], v[82:85]
	v_mfma_f32_16x16x32_bf16 v[38:41], v[248:251], v[118:121], v[38:41]
	ds_read_b128 v[248:251], v1 offset:28928
	s_waitcnt lgkmcnt(2)
	v_mfma_f32_16x16x32_bf16 v[62:65], v[122:125], v[114:117], v[62:65]
	v_mfma_f32_16x16x32_bf16 v[46:49], v[122:125], v[118:121], v[46:49]
	ds_read_b128 v[122:125], v1 offset:31232
	s_waitcnt lgkmcnt(2)
	v_mfma_f32_16x16x32_bf16 v[66:69], v[244:247], v[114:117], v[66:69]
	v_mfma_f32_16x16x32_bf16 v[50:53], v[244:247], v[118:121], v[50:53]
	ds_read_b128 v[244:247], v1 offset:33536
	s_waitcnt lgkmcnt(2)
	v_mfma_f32_16x16x32_bf16 v[70:73], v[248:251], v[114:117], v[70:73]
	v_mfma_f32_16x16x32_bf16 v[54:57], v[248:251], v[118:121], v[54:57]
	ds_read_b128 v[248:251], v1 offset:17472
	s_waitcnt lgkmcnt(2)
	v_mfma_f32_16x16x32_bf16 v[74:77], v[122:125], v[114:117], v[74:77]
	v_mfma_f32_16x16x32_bf16 v[58:61], v[122:125], v[118:121], v[58:61]
	ds_read_b128 v[122:125], v1 offset:19776
	s_waitcnt lgkmcnt(2)
	v_mfma_f32_16x16x32_bf16 v[90:93], v[244:247], v[114:117], v[90:93]
	v_cvt_pk_bf16_f32 v114, v130, v132
	v_cvt_pk_bf16_f32 v115, v134, v136
	v_cvt_pk_bf16_f32 v116, v138, v140
	v_mfma_f32_16x16x32_bf16 v[78:81], v[244:247], v[118:121], v[78:81]
	ds_read_b128 v[244:247], v1 offset:22080
	v_cvt_pk_bf16_f32 v118, v131, v133
	v_cvt_pk_bf16_f32 v119, v135, v137
	v_cvt_pk_bf16_f32 v120, v139, v141
	v_cvt_pk_bf16_f32 v121, v143, v145
	v_cvt_pk_bf16_f32 v117, v142, v144
	s_waitcnt lgkmcnt(2)
	v_mfma_f32_16x16x32_bf16 v[94:97], v[248:251], v[118:121], v[94:97]
	v_mfma_f32_16x16x32_bf16 v[42:45], v[248:251], v[114:117], v[42:45]
	ds_read_b128 v[248:251], v1 offset:24384
	s_waitcnt lgkmcnt(2)
	v_mfma_f32_16x16x32_bf16 v[86:89], v[122:125], v[118:121], v[86:89]
	v_mfma_f32_16x16x32_bf16 v[34:37], v[122:125], v[114:117], v[34:37]
	ds_read_b128 v[122:125], v1 offset:26688
	s_waitcnt lgkmcnt(2)
	v_mfma_f32_16x16x32_bf16 v[82:85], v[244:247], v[118:121], v[82:85]
	v_mfma_f32_16x16x32_bf16 v[38:41], v[244:247], v[114:117], v[38:41]
	ds_read_b128 v[244:247], v1 offset:28992
	s_waitcnt lgkmcnt(2)
	v_mfma_f32_16x16x32_bf16 v[62:65], v[248:251], v[118:121], v[62:65]
	v_mfma_f32_16x16x32_bf16 v[46:49], v[248:251], v[114:117], v[46:49]
	ds_read_b128 v[248:251], v1 offset:31296
	s_waitcnt lgkmcnt(2)
	v_mfma_f32_16x16x32_bf16 v[66:69], v[122:125], v[118:121], v[66:69]
	v_mfma_f32_16x16x32_bf16 v[50:53], v[122:125], v[114:117], v[50:53]
	ds_read_b128 v[122:125], v1 offset:33600
	s_waitcnt lgkmcnt(2)
	v_mfma_f32_16x16x32_bf16 v[70:73], v[244:247], v[118:121], v[70:73]
	v_mfma_f32_16x16x32_bf16 v[54:57], v[244:247], v[114:117], v[54:57]
	s_waitcnt lgkmcnt(1)
	v_mfma_f32_16x16x32_bf16 v[74:77], v[248:251], v[118:121], v[74:77]
	v_mfma_f32_16x16x32_bf16 v[58:61], v[248:251], v[114:117], v[58:61]
	v_cndmask_b32_e64 v1, 0, 1, s[22:23]
	s_waitcnt lgkmcnt(0)
	v_mfma_f32_16x16x32_bf16 v[90:93], v[122:125], v[118:121], v[90:93]
	v_readfirstlane_b32 s10, v1
	s_xor_b32 s31, s31, s10
	s_barrier
	v_mfma_f32_16x16x32_bf16 v[78:81], v[122:125], v[114:117], v[78:81]
	s_cbranch_vccz .LBB0_136
	s_mov_b32 s24, s17
	s_mov_b32 s17, s34
	s_branch .LBB0_124

.LBB0_141:
	v_cmp_ngt_f32_e32 vcc, s2, v168
	v_add_u32_e32 v1, v1, v204
	s_xor_b32 s5, s5, 1
	v_cndmask_b32_e32 v169, 0, v168, vcc
	v_sub_f32_e32 v130, v130, v169
	v_exp_f32_e32 v171, v130
	v_sub_f32_e32 v130, v131, v169
	v_exp_f32_e32 v173, v130
	v_sub_f32_e32 v130, v132, v169
	v_exp_f32_e32 v175, v130
	v_sub_f32_e32 v130, v133, v169
	v_exp_f32_e32 v177, v130
	v_sub_f32_e32 v130, v134, v169
	v_exp_f32_e32 v179, v130
	v_sub_f32_e32 v130, v135, v169
	v_exp_f32_e32 v181, v130
	v_sub_f32_e32 v130, v136, v169
	v_exp_f32_e32 v183, v130
	v_sub_f32_e32 v130, v137, v169
	v_exp_f32_e32 v185, v130
	v_sub_f32_e32 v130, v138, v169
	v_exp_f32_e32 v131, v130
	v_sub_f32_e32 v130, v139, v169
	v_exp_f32_e32 v133, v130
	v_sub_f32_e32 v130, v140, v169
	v_exp_f32_e32 v135, v130
	v_sub_f32_e32 v130, v141, v169
	v_exp_f32_e32 v137, v130
	v_sub_f32_e32 v130, v142, v169
	v_exp_f32_e32 v139, v130
	v_sub_f32_e32 v130, v143, v169
	v_cmp_ngt_f32_e32 vcc, s2, v165
	v_exp_f32_e32 v141, v130
	v_sub_f32_e32 v130, v144, v169
	v_cndmask_b32_e32 v144, 0, v165, vcc
	v_sub_f32_e32 v114, v114, v144
	v_exp_f32_e32 v170, v114
	v_sub_f32_e32 v114, v115, v144
	v_exp_f32_e32 v172, v114
	v_sub_f32_e32 v114, v116, v144
	v_exp_f32_e32 v174, v114
	v_sub_f32_e32 v114, v117, v144
	v_exp_f32_e32 v176, v114
	v_sub_f32_e32 v114, v118, v144
	v_exp_f32_e32 v178, v114
	v_sub_f32_e32 v114, v119, v144
	v_exp_f32_e32 v180, v114
	v_sub_f32_e32 v114, v120, v144
	v_exp_f32_e32 v182, v114
	v_pk_add_f32 v[114:115], v[170:171], 0 op_sel_hi:[1,0]
	v_sub_f32_e32 v116, v121, v144
	v_pk_add_f32 v[114:115], v[172:173], v[114:115]
	v_exp_f32_e32 v143, v130
	v_pk_add_f32 v[114:115], v[174:175], v[114:115]
	v_sub_f32_e32 v130, v145, v169
	v_pk_add_f32 v[114:115], v[176:177], v[114:115]
	v_exp_f32_e32 v184, v116
	v_sub_f32_e32 v116, v122, v144
	v_exp_f32_e32 v145, v130
	v_pk_add_f32 v[114:115], v[178:179], v[114:115]
	v_exp_f32_e32 v130, v116
	v_sub_f32_e32 v116, v123, v144
	v_pk_add_f32 v[114:115], v[180:181], v[114:115]
	v_exp_f32_e32 v132, v116
	v_sub_f32_e32 v116, v124, v144
	v_pk_add_f32 v[114:115], v[182:183], v[114:115]
	v_exp_f32_e32 v134, v116
	v_sub_f32_e32 v116, v125, v144
	v_exp_f32_e32 v136, v116
	v_sub_f32_e32 v116, v126, v144
	v_pk_add_f32 v[114:115], v[184:185], v[114:115]
	v_exp_f32_e32 v138, v116
	v_sub_f32_e32 v116, v127, v144
	v_pk_add_f32 v[114:115], v[130:131], v[114:115]
	ds_read_b128 v[122:125], v1 offset:17408
	ds_read_b128 v[244:247], v1 offset:19712
	ds_read_b128 v[248:251], v1 offset:22016
	v_exp_f32_e32 v140, v116
	v_sub_f32_e32 v116, v128, v144
	v_pk_add_f32 v[114:115], v[132:133], v[114:115]
	v_exp_f32_e32 v142, v116
	v_sub_f32_e32 v116, v129, v144
	v_pk_add_f32 v[114:115], v[134:135], v[114:115]
	v_exp_f32_e32 v144, v116
	v_pk_add_f32 v[114:115], v[136:137], v[114:115]
	v_cvt_pk_bf16_f32 v116, v179, v181
	v_pk_add_f32 v[114:115], v[138:139], v[114:115]
	v_cvt_pk_bf16_f32 v117, v183, v185
	v_pk_add_f32 v[114:115], v[140:141], v[114:115]
	v_cvt_pk_bf16_f32 v118, v170, v172
	v_pk_add_f32 v[114:115], v[142:143], v[114:115]
	v_cvt_pk_bf16_f32 v119, v174, v176
	v_pk_add_f32 v[114:115], v[144:145], v[114:115]
	v_cvt_pk_bf16_f32 v120, v178, v180
	v_pk_add_f32 v[152:153], v[152:153], v[114:115]
	v_cvt_pk_bf16_f32 v114, v171, v173
	v_cvt_pk_bf16_f32 v115, v175, v177
	v_cvt_pk_bf16_f32 v121, v182, v184
	s_mov_b64 s[2:3], 0xa0000
	s_waitcnt lgkmcnt(2)
	v_mfma_f32_16x16x32_bf16 v[94:97], v[122:125], v[114:117], v[94:97]
	v_lshl_add_u64 v[166:167], v[166:167], 0, s[6:7]
	v_lshl_add_u64 v[162:163], v[162:163], 0, s[6:7]
	v_lshl_add_u64 v[154:155], v[154:155], 0, s[2:3]
	v_mfma_f32_16x16x32_bf16 v[42:45], v[122:125], v[118:121], v[42:45]
	ds_read_b128 v[122:125], v1 offset:24320
	v_lshl_add_u64 v[156:157], v[156:157], 0, s[2:3]
	v_subrev_u32_e32 v164, 64, v164
	s_waitcnt lgkmcnt(2)
	v_mfma_f32_16x16x32_bf16 v[86:89], v[244:247], v[114:117], v[86:89]
	s_and_b64 vcc, exec, s[34:35]
	v_mfma_f32_16x16x32_bf16 v[34:37], v[244:247], v[118:121], v[34:37]
	ds_read_b128 v[244:247], v1 offset:26624
	s_waitcnt lgkmcnt(2)
	v_mfma_f32_16x16x32_bf16 v[82:85], v[248:251], v[114:117], v[82:85]
	v_mfma_f32_16x16x32_bf16 v[38:41], v[248:251], v[118:121], v[38:41]
	ds_read_b128 v[248:251], v1 offset:28928
	s_waitcnt lgkmcnt(2)
	v_mfma_f32_16x16x32_bf16 v[62:65], v[122:125], v[114:117], v[62:65]
	v_mfma_f32_16x16x32_bf16 v[46:49], v[122:125], v[118:121], v[46:49]
	ds_read_b128 v[122:125], v1 offset:31232
	s_waitcnt lgkmcnt(2)
	v_mfma_f32_16x16x32_bf16 v[66:69], v[244:247], v[114:117], v[66:69]
	v_mfma_f32_16x16x32_bf16 v[50:53], v[244:247], v[118:121], v[50:53]
	ds_read_b128 v[244:247], v1 offset:33536
	s_waitcnt lgkmcnt(2)
	v_mfma_f32_16x16x32_bf16 v[70:73], v[248:251], v[114:117], v[70:73]
	v_mfma_f32_16x16x32_bf16 v[54:57], v[248:251], v[118:121], v[54:57]
	ds_read_b128 v[248:251], v1 offset:17472
	s_waitcnt lgkmcnt(2)
	v_mfma_f32_16x16x32_bf16 v[74:77], v[122:125], v[114:117], v[74:77]
	v_mfma_f32_16x16x32_bf16 v[58:61], v[122:125], v[118:121], v[58:61]
	ds_read_b128 v[122:125], v1 offset:19776
	s_waitcnt lgkmcnt(2)
	v_mfma_f32_16x16x32_bf16 v[90:93], v[244:247], v[114:117], v[90:93]
	v_cvt_pk_bf16_f32 v114, v130, v132
	v_cvt_pk_bf16_f32 v115, v134, v136
	v_cvt_pk_bf16_f32 v116, v138, v140
	v_mfma_f32_16x16x32_bf16 v[78:81], v[244:247], v[118:121], v[78:81]
	ds_read_b128 v[244:247], v1 offset:22080
	v_cvt_pk_bf16_f32 v118, v131, v133
	v_cvt_pk_bf16_f32 v119, v135, v137
	v_cvt_pk_bf16_f32 v120, v139, v141
	v_cvt_pk_bf16_f32 v121, v143, v145
	v_cvt_pk_bf16_f32 v117, v142, v144
	s_waitcnt lgkmcnt(2)
	v_mfma_f32_16x16x32_bf16 v[94:97], v[248:251], v[118:121], v[94:97]
	v_mfma_f32_16x16x32_bf16 v[42:45], v[248:251], v[114:117], v[42:45]
	ds_read_b128 v[248:251], v1 offset:24384
	s_waitcnt lgkmcnt(2)
	v_mfma_f32_16x16x32_bf16 v[86:89], v[122:125], v[118:121], v[86:89]
	v_mfma_f32_16x16x32_bf16 v[34:37], v[122:125], v[114:117], v[34:37]
	ds_read_b128 v[122:125], v1 offset:26688
	s_waitcnt lgkmcnt(2)
	v_mfma_f32_16x16x32_bf16 v[82:85], v[244:247], v[118:121], v[82:85]
	v_mfma_f32_16x16x32_bf16 v[38:41], v[244:247], v[114:117], v[38:41]
	ds_read_b128 v[244:247], v1 offset:28992
	s_waitcnt lgkmcnt(2)
	v_mfma_f32_16x16x32_bf16 v[62:65], v[248:251], v[118:121], v[62:65]
	v_mfma_f32_16x16x32_bf16 v[46:49], v[248:251], v[114:117], v[46:49]
	ds_read_b128 v[248:251], v1 offset:31296
	s_waitcnt lgkmcnt(2)
	v_mfma_f32_16x16x32_bf16 v[66:69], v[122:125], v[118:121], v[66:69]
	v_mfma_f32_16x16x32_bf16 v[50:53], v[122:125], v[114:117], v[50:53]
	ds_read_b128 v[122:125], v1 offset:33600
	s_waitcnt lgkmcnt(2)
	v_mfma_f32_16x16x32_bf16 v[70:73], v[244:247], v[118:121], v[70:73]
	v_mfma_f32_16x16x32_bf16 v[54:57], v[244:247], v[114:117], v[54:57]
	s_waitcnt lgkmcnt(1)
	v_mfma_f32_16x16x32_bf16 v[74:77], v[248:251], v[118:121], v[74:77]
	v_mfma_f32_16x16x32_bf16 v[58:61], v[248:251], v[114:117], v[58:61]
	s_waitcnt lgkmcnt(0)
	s_barrier
	v_mfma_f32_16x16x32_bf16 v[90:93], v[122:125], v[118:121], v[90:93]
	v_mfma_f32_16x16x32_bf16 v[78:81], v[122:125], v[114:117], v[78:81]
	s_cbranch_vccnz .LBB0_99

.LBB0_145:
	s_cmp_lt_i32 s4, s42
	s_cselect_b64 s[12:13], -1, 0
	s_xor_b64 s[10:11], s[10:11], -1
	s_or_b64 s[36:37], s[10:11], s[12:13]
	s_cmp_eq_u32 s5, 0
	s_cselect_b32 s10, 0, 0x11c00
	v_add_u32_e32 v1, s10, v192
	v_add_u32_e32 v169, v1, v198
	ds_read_b128 v[170:173], v169
	ds_read_b128 v[244:247], v169 offset:64
	ds_read_b128 v[248:251], v169 offset:128
	v_add_u32_e32 v176, 34, v164
	v_add_u32_e32 v174, 33, v164
	v_add_u32_e32 v178, 19, v164
	v_add_u32_e32 v177, 18, v164
	v_add_u32_e32 v175, 17, v164
	v_add_u32_e32 v179, 16, v164
	s_and_b64 vcc, exec, s[36:37]
	v_cmp_lt_u32_e64 s[18:19], s92, v176
	v_cmp_lt_u32_e64 s[20:21], s92, v174
	v_cmp_lt_u32_e64 s[24:25], s92, v178
	v_cmp_lt_u32_e64 s[26:27], s92, v177
	v_cmp_lt_u32_e64 s[28:29], s92, v175
	v_cmp_lt_u32_e64 s[30:31], s92, v179
	s_waitcnt lgkmcnt(2)
	v_mfma_f32_16x16x32_bf16 v[130:133], v[170:173], v[2:5], 0
	v_mfma_f32_16x16x32_bf16 v[114:117], v[170:173], v[18:21], 0
	ds_read_b128 v[170:173], v169 offset:192
	s_waitcnt lgkmcnt(2)
	v_mfma_f32_16x16x32_bf16 v[130:133], v[244:247], v[6:9], v[130:133]
	v_mfma_f32_16x16x32_bf16 v[114:117], v[244:247], v[22:25], v[114:117]
	ds_read_b128 v[244:247], v169 offset:4352
	s_waitcnt lgkmcnt(2)
	v_mfma_f32_16x16x32_bf16 v[130:133], v[248:251], v[10:13], v[130:133]
	v_mfma_f32_16x16x32_bf16 v[114:117], v[248:251], v[26:29], v[114:117]
	ds_read_b128 v[248:251], v169 offset:4416
	s_waitcnt lgkmcnt(2)
	v_mfma_f32_16x16x32_bf16 v[130:133], v[170:173], v[14:17], v[130:133]
	v_mfma_f32_16x16x32_bf16 v[114:117], v[170:173], v[30:33], v[114:117]
	ds_read_b128 v[170:173], v169 offset:4480
	s_waitcnt lgkmcnt(2)
	v_mfma_f32_16x16x32_bf16 v[134:137], v[244:247], v[2:5], 0
	v_mfma_f32_16x16x32_bf16 v[118:121], v[244:247], v[18:21], 0
	ds_read_b128 v[244:247], v169 offset:4544
	s_waitcnt lgkmcnt(2)
	v_mfma_f32_16x16x32_bf16 v[134:137], v[248:251], v[6:9], v[134:137]
	v_mfma_f32_16x16x32_bf16 v[118:121], v[248:251], v[22:25], v[118:121]
	ds_read_b128 v[248:251], v169 offset:8704
	s_waitcnt lgkmcnt(2)
	v_mfma_f32_16x16x32_bf16 v[134:137], v[170:173], v[10:13], v[134:137]
	v_mfma_f32_16x16x32_bf16 v[118:121], v[170:173], v[26:29], v[118:121]
	ds_read_b128 v[170:173], v169 offset:8768
	s_waitcnt lgkmcnt(2)
	v_mfma_f32_16x16x32_bf16 v[134:137], v[244:247], v[14:17], v[134:137]
	v_mfma_f32_16x16x32_bf16 v[118:121], v[244:247], v[30:33], v[118:121]
	ds_read_b128 v[244:247], v169 offset:8832
	s_waitcnt lgkmcnt(2)
	v_mfma_f32_16x16x32_bf16 v[138:141], v[248:251], v[2:5], 0
	v_mfma_f32_16x16x32_bf16 v[122:125], v[248:251], v[18:21], 0
	ds_read_b128 v[248:251], v169 offset:8896
	s_waitcnt lgkmcnt(2)
	v_mfma_f32_16x16x32_bf16 v[138:141], v[170:173], v[6:9], v[138:141]
	v_mfma_f32_16x16x32_bf16 v[122:125], v[170:173], v[22:25], v[122:125]
	ds_read_b128 v[170:173], v169 offset:13056
	s_waitcnt lgkmcnt(2)
	v_mfma_f32_16x16x32_bf16 v[138:141], v[244:247], v[10:13], v[138:141]
	v_mfma_f32_16x16x32_bf16 v[122:125], v[244:247], v[26:29], v[122:125]
	ds_read_b128 v[244:247], v169 offset:13120
	s_waitcnt lgkmcnt(2)
	v_mfma_f32_16x16x32_bf16 v[138:141], v[248:251], v[14:17], v[138:141]
	v_mfma_f32_16x16x32_bf16 v[122:125], v[248:251], v[30:33], v[122:125]
	ds_read_b128 v[248:251], v169 offset:13184
	s_waitcnt lgkmcnt(2)
	v_mfma_f32_16x16x32_bf16 v[142:145], v[170:173], v[2:5], 0
	v_mfma_f32_16x16x32_bf16 v[126:129], v[170:173], v[18:21], 0
	ds_read_b128 v[170:173], v169 offset:13248
	s_waitcnt lgkmcnt(2)
	v_mfma_f32_16x16x32_bf16 v[142:145], v[244:247], v[6:9], v[142:145]
	v_mfma_f32_16x16x32_bf16 v[126:129], v[244:247], v[22:25], v[126:129]
	s_waitcnt lgkmcnt(1)
	v_mfma_f32_16x16x32_bf16 v[142:145], v[248:251], v[10:13], v[142:145]
	v_mfma_f32_16x16x32_bf16 v[126:129], v[248:251], v[26:29], v[126:129]
	s_waitcnt lgkmcnt(0)
	v_mfma_f32_16x16x32_bf16 v[142:145], v[170:173], v[14:17], v[142:145]
	v_mfma_f32_16x16x32_bf16 v[126:129], v[170:173], v[30:33], v[126:129]
	v_add_u32_e32 v169, 50, v164
	v_cmp_lt_u32_e64 s[10:11], s92, v169
	v_add_u32_e32 v173, 49, v164
	v_add_u32_e32 v171, 48, v164
	v_add_u32_e32 v170, 35, v164
	v_add_u32_e32 v172, 32, v164
	v_cmp_lt_u32_e64 s[12:13], s92, v173
	v_cmp_lt_u32_e64 s[14:15], s92, v171
	v_cmp_lt_u32_e64 s[16:17], s92, v170
	v_cmp_lt_u32_e64 s[22:23], s92, v172
	s_cbranch_vccz .LBB0_147
	v_add_u32_e32 v180, 0x233, v164
	s_movk_i32 s2, 0x200
	v_cmp_gt_u32_e32 vcc, s2, v180
	v_add_u32_e32 v180, 3, v164
	v_cndmask_b32_e64 v131, v227, v131, s[10:11]
	v_cndmask_b32_e32 v130, v227, v130, vcc
	v_cmp_lt_u32_e32 vcc, s92, v180
	v_add_u32_e32 v180, 2, v164
	v_cndmask_b32_e64 v132, v227, v132, s[12:13]
	v_cndmask_b32_e32 v142, v227, v142, vcc
	v_cmp_lt_u32_e32 vcc, s92, v180
	v_add_u32_e32 v180, 1, v164
	v_cndmask_b32_e64 v133, v227, v133, s[14:15]
	v_cndmask_b32_e32 v143, v227, v143, vcc
	v_cmp_lt_u32_e32 vcc, s92, v180
	v_cndmask_b32_e64 v134, v227, v134, s[16:17]
	v_cndmask_b32_e64 v135, v227, v135, s[18:19]
	v_cndmask_b32_e32 v144, v227, v144, vcc
	v_cmp_lt_u32_e32 vcc, s92, v164
	v_cndmask_b32_e64 v136, v227, v136, s[20:21]
	v_cndmask_b32_e64 v137, v227, v137, s[22:23]
	v_cndmask_b32_e64 v138, v227, v138, s[24:25]
	v_cndmask_b32_e64 v139, v227, v139, s[26:27]
	v_cndmask_b32_e64 v140, v227, v140, s[28:29]
	v_cndmask_b32_e64 v141, v227, v141, s[30:31]
	v_cndmask_b32_e32 v145, v227, v145, vcc

.LBB0_351:
	global_load_dwordx4 v[48:51], v[46:47], off offset:256
	global_load_dwordx4 v[58:61], v[46:47], off offset:272
	s_mov_b32 s1, 0x5040100
	s_waitcnt vmcnt(1)
	v_cndmask_b32_e64 v1, v48, 0, s[56:57]
	v_cndmask_b32_e64 v48, 0, v49, s[90:91]
	v_cvt_pk_bf16_f32 v48, v1, v48
	v_cvt_pk_bf16_f32 v1, v50, v51
	v_cndmask_b32_e64 v49, v1, 0, s[4:5]
	v_lshrrev_b32_e32 v1, 16, v1
	v_cndmask_b32_e64 v1, v1, 0, s[2:3]
	v_perm_b32 v49, v1, v49, s1
	s_waitcnt vmcnt(0)
	v_cvt_pk_bf16_f32 v1, v58, v59
	v_cndmask_b32_e64 v50, v1, 0, s[86:87]
	v_lshrrev_b32_e32 v1, 16, v1
	v_cndmask_b32_e64 v1, v1, 0, s[84:85]
	v_perm_b32 v50, v1, v50, s1
	v_cvt_pk_bf16_f32 v1, v60, v61
	ds_read_b128 v[248:251], v57 offset:128
	ds_read_b128 v[58:61], v57 offset:4480
	ds_read_b128 v[244:247], v57 offset:8832
	v_cndmask_b32_e64 v51, v1, 0, s[8:9]
	v_lshrrev_b32_e32 v1, 16, v1
	v_cndmask_b32_e64 v1, v1, 0, s[96:97]
	v_perm_b32 v51, v1, v51, s1
	s_waitcnt lgkmcnt(2)
	s_nop 0
	v_mfma_f32_16x16x32_bf16 v[30:33], v[248:251], v[48:51], v[30:33]
	ds_read_b128 v[248:251], v57 offset:13184
	s_waitcnt lgkmcnt(2)
	v_mfma_f32_16x16x32_bf16 v[26:29], v[58:61], v[48:51], v[26:29]
	ds_read_b128 v[58:61], v57 offset:17536
	s_waitcnt lgkmcnt(2)
	v_mfma_f32_16x16x32_bf16 v[22:25], v[244:247], v[48:51], v[22:25]
	ds_read_b128 v[244:247], v57 offset:21888
	s_waitcnt lgkmcnt(2)
	v_mfma_f32_16x16x32_bf16 v[18:21], v[248:251], v[48:51], v[18:21]
	ds_read_b128 v[248:251], v57 offset:26240
	s_waitcnt lgkmcnt(2)
	v_mfma_f32_16x16x32_bf16 v[14:17], v[58:61], v[48:51], v[14:17]
	ds_read_b128 v[58:61], v57 offset:30592
	s_waitcnt lgkmcnt(2)
	v_mfma_f32_16x16x32_bf16 v[10:13], v[244:247], v[48:51], v[10:13]
	s_waitcnt lgkmcnt(1)
	v_mfma_f32_16x16x32_bf16 v[6:9], v[248:251], v[48:51], v[6:9]
	s_waitcnt lgkmcnt(0)
	v_mfma_f32_16x16x32_bf16 v[2:5], v[58:61], v[48:51], v[2:5]
	s_or_b64 exec, exec, s[82:83]
	s_and_saveexec_b64 s[82:83], s[64:65]
	s_cbranch_execz .LBB0_347
	s_branch .LBB0_355

.LBB0_353:
	global_load_dwordx4 v[48:51], v[46:47], off offset:128
	global_load_dwordx4 v[58:61], v[46:47], off offset:144
	s_mov_b32 s1, 0x5040100
	s_waitcnt vmcnt(1)
	v_cndmask_b32_e64 v1, v48, 0, s[28:29]
	v_cndmask_b32_e64 v48, 0, v49, s[30:31]
	v_cvt_pk_bf16_f32 v48, v1, v48
	v_cvt_pk_bf16_f32 v1, v50, v51
	v_cndmask_b32_e64 v49, v1, 0, s[36:37]
	v_lshrrev_b32_e32 v1, 16, v1
	v_cndmask_b32_e64 v1, v1, 0, s[34:35]
	v_perm_b32 v49, v1, v49, s1
	s_waitcnt vmcnt(0)
	v_cvt_pk_bf16_f32 v1, v58, v59
	v_cndmask_b32_e64 v50, v1, 0, s[40:41]
	v_lshrrev_b32_e32 v1, 16, v1
	v_cndmask_b32_e64 v1, v1, 0, s[38:39]
	v_perm_b32 v50, v1, v50, s1
	v_cvt_pk_bf16_f32 v1, v60, v61
	ds_read_b128 v[248:251], v57 offset:64
	ds_read_b128 v[58:61], v57 offset:4416
	ds_read_b128 v[244:247], v57 offset:8768
	v_cndmask_b32_e64 v51, v1, 0, s[44:45]
	v_lshrrev_b32_e32 v1, 16, v1
	v_cndmask_b32_e64 v1, v1, 0, s[42:43]
	v_perm_b32 v51, v1, v51, s1
	s_waitcnt lgkmcnt(2)
	s_nop 0
	v_mfma_f32_16x16x32_bf16 v[30:33], v[248:251], v[48:51], v[30:33]
	ds_read_b128 v[248:251], v57 offset:13120
	s_waitcnt lgkmcnt(2)
	v_mfma_f32_16x16x32_bf16 v[26:29], v[58:61], v[48:51], v[26:29]
	ds_read_b128 v[58:61], v57 offset:17472
	s_waitcnt lgkmcnt(2)
	v_mfma_f32_16x16x32_bf16 v[22:25], v[244:247], v[48:51], v[22:25]
	ds_read_b128 v[244:247], v57 offset:21824
	s_waitcnt lgkmcnt(2)
	v_mfma_f32_16x16x32_bf16 v[18:21], v[248:251], v[48:51], v[18:21]
	ds_read_b128 v[248:251], v57 offset:26176
	s_waitcnt lgkmcnt(2)
	v_mfma_f32_16x16x32_bf16 v[14:17], v[58:61], v[48:51], v[14:17]
	ds_read_b128 v[58:61], v57 offset:30528
	s_waitcnt lgkmcnt(2)
	v_mfma_f32_16x16x32_bf16 v[10:13], v[244:247], v[48:51], v[10:13]
	s_waitcnt lgkmcnt(1)
	v_mfma_f32_16x16x32_bf16 v[6:9], v[248:251], v[48:51], v[6:9]
	s_waitcnt lgkmcnt(0)
	v_mfma_f32_16x16x32_bf16 v[2:5], v[58:61], v[48:51], v[2:5]
	s_or_b64 exec, exec, s[82:83]
	s_and_saveexec_b64 s[82:83], s[46:47]
	s_cbranch_execnz .LBB0_351

.LBB0_355:
	global_load_dwordx4 v[48:51], v[46:47], off offset:384
	global_load_dwordx4 v[58:61], v[46:47], off offset:400
	s_mov_b32 s1, 0x5040100
	s_waitcnt vmcnt(1)
	v_cndmask_b32_e64 v1, v48, 0, s[66:67]
	v_cndmask_b32_e64 v46, 0, v49, s[68:69]
	v_cvt_pk_bf16_f32 v46, v1, v46
	v_cvt_pk_bf16_f32 v1, v50, v51
	v_cndmask_b32_e64 v47, v1, 0, s[72:73]
	v_lshrrev_b32_e32 v1, 16, v1
	ds_read_b128 v[50:53], v57 offset:192
	v_cndmask_b32_e64 v1, v1, 0, s[70:71]
	v_perm_b32 v47, v1, v47, s1
	s_waitcnt vmcnt(0)
	v_cvt_pk_bf16_f32 v1, v58, v59
	v_cndmask_b32_e64 v48, v1, 0, s[76:77]
	v_lshrrev_b32_e32 v1, 16, v1
	v_cndmask_b32_e64 v1, v1, 0, s[74:75]
	v_perm_b32 v48, v1, v48, s1
	v_cvt_pk_bf16_f32 v1, v60, v61
	v_cndmask_b32_e64 v49, v1, 0, s[80:81]
	v_lshrrev_b32_e32 v1, 16, v1
	v_cndmask_b32_e64 v1, v1, 0, s[78:79]
	v_perm_b32 v49, v1, v49, s1
	s_waitcnt lgkmcnt(0)
	s_nop 0
	v_mfma_f32_16x16x32_bf16 v[30:33], v[50:53], v[46:49], v[30:33]
	ds_read_b128 v[50:53], v57 offset:4544
	ds_read_b128 v[244:247], v57 offset:8896
	ds_read_b128 v[248:251], v57 offset:13248
	s_waitcnt lgkmcnt(2)
	v_mfma_f32_16x16x32_bf16 v[26:29], v[50:53], v[46:49], v[26:29]
	ds_read_b128 v[50:53], v57 offset:17600
	s_waitcnt lgkmcnt(2)
	v_mfma_f32_16x16x32_bf16 v[22:25], v[244:247], v[46:49], v[22:25]
	ds_read_b128 v[244:247], v57 offset:21952
	s_waitcnt lgkmcnt(2)
	v_mfma_f32_16x16x32_bf16 v[18:21], v[248:251], v[46:49], v[18:21]
	ds_read_b128 v[248:251], v57 offset:26304
	s_waitcnt lgkmcnt(2)
	v_mfma_f32_16x16x32_bf16 v[14:17], v[50:53], v[46:49], v[14:17]
	ds_read_b128 v[50:53], v57 offset:30656
	s_waitcnt lgkmcnt(2)
	v_mfma_f32_16x16x32_bf16 v[10:13], v[244:247], v[46:49], v[10:13]
	s_waitcnt lgkmcnt(1)
	v_mfma_f32_16x16x32_bf16 v[6:9], v[248:251], v[46:49], v[6:9]
	s_waitcnt lgkmcnt(0)
	v_mfma_f32_16x16x32_bf16 v[2:5], v[50:53], v[46:49], v[2:5]
	s_branch .LBB0_347

.LBB0_916:
	v_readlane_b32 s2, v253, 8
	v_readlane_b32 s3, v253, 9
	s_sleep 8
	s_mov_b64 s[12:13], -1
	s_nop 2
	global_load_dword v1, v0, s[2:3] sc1
	s_waitcnt vmcnt(0)
	v_cmp_le_u32_e32 vcc, s5, v1
	s_cbranch_vccnz .LBB0_915
	v_readlane_b32 s2, v253, 8
	v_readlane_b32 s3, v253, 9
	s_sleep 8
	s_nop 3
	global_load_dword v1, v0, s[2:3] sc1
	s_waitcnt vmcnt(0)
	v_cmp_gt_u32_e32 vcc, s5, v1
	s_cbranch_vccz .LBB0_915
	v_readlane_b32 s2, v253, 8
	v_readlane_b32 s3, v253, 9
	s_sleep 8
	s_nop 3
	global_load_dword v1, v0, s[2:3] sc1
	s_waitcnt vmcnt(0)
	v_cmp_gt_u32_e32 vcc, s5, v1
	s_cbranch_vccz .LBB0_915
	v_readlane_b32 s2, v253, 8
	v_readlane_b32 s3, v253, 9
	s_sleep 8
	s_nop 3
	global_load_dword v1, v0, s[2:3] sc1
	s_waitcnt vmcnt(0)
	v_cmp_gt_u32_e32 vcc, s5, v1
	s_cbranch_vccz .LBB0_915
	v_readlane_b32 s2, v253, 8
	v_readlane_b32 s3, v253, 9
	s_sleep 8
	s_nop 3
	global_load_dword v1, v0, s[2:3] sc1
	s_waitcnt vmcnt(0)
	v_cmp_gt_u32_e32 vcc, s5, v1
	s_cbranch_vccz .LBB0_915
	v_readlane_b32 s2, v253, 8
	v_readlane_b32 s3, v253, 9
	s_sleep 8
	s_nop 3
	global_load_dword v1, v0, s[2:3] sc1
	s_waitcnt vmcnt(0)
	v_cmp_gt_u32_e32 vcc, s5, v1
	s_cbranch_vccz .LBB0_915
	v_readlane_b32 s2, v253, 8
	v_readlane_b32 s3, v253, 9
	s_sleep 8
	s_cmp_eq_u32 s14, 0
	s_cselect_b64 s[12:13], -1, 0
	s_nop 1
	global_load_dword v1, v0, s[2:3] sc1
	s_waitcnt vmcnt(0)
	v_cmp_le_u32_e32 vcc, s5, v1
	s_or_b64 s[12:13], vcc, s[12:13]
	s_andn2_b64 vcc, exec, s[12:13]
	s_mov_b64 s[12:13], -1
	s_cbranch_vccz .LBB0_915
	v_readlane_b32 s2, v253, 8
	v_readlane_b32 s3, v253, 9
	s_sleep 8
	s_add_i32 s14, s14, -8
	s_nop 2
	global_load_dword v1, v0, s[2:3] sc1
	s_waitcnt vmcnt(0)
	v_cmp_le_u32_e64 s[12:13], s5, v1
	s_branch .LBB0_915
